# LayerNorm: a workgroup's 8 waves take their rows from a shared LDS counter (faster waves take more rows); same rows, same arithmetic
# baseline (speedup 1.0000x reference)
; DI float bflo(unsigned w) { return __uint_as_float(w << 16); }
; DI float bfhi(unsigned w) { return __uint_as_float(w & 0xffff0000u); }
; DI void phase_ln(const Params& p, int layer) {
;     ...
;   int tid_ = threadIdx.x; asm volatile("" : "+v"(tid_)); const int tid = tid_, lane = tid & 63, w = tid >> 6;
; #pragma unroll 1
;   for (size_t row = (size_t)blockIdx.x * 8 + w; row < (size_t)T; row += (size_t)gridDim.x * 8) {
;     f32x4 v[4]; float sum = 0.f;
; #pragma unroll
;     for (int i = 0; i < 4; ++i) {
;       const f32x4 xv = *(const f32x4*)(xres + row * DM + 4 * lane + 256 * i);
;       const u32x2 yw = *(const u32x2*)(xb + row * DM + 4 * lane + 256 * i);
;       v[i][0] = ALPHA * xv[0] + bflo(yw[0]); v[i][1] = ALPHA * xv[1] + bfhi(yw[0]); v[i][2] = ALPHA * xv[2] + bflo(yw[1]); v[i][3] = ALPHA * xv[3] + bfhi(yw[1]);
;       sum += v[i][0] + v[i][1] + v[i][2] + v[i][3];
;     }
;     const float mu = wave_sum(sum) * (1.f / DM);
.LBB0_540:
	s_or_b64 exec, exec, s[4:5]
	v_mov_b32_e32 v2, v184
	v_cmp_eq_u32_e32 vcc, 0, v184
	s_and_saveexec_b64 s[4:5], vcc
	v_mov_b32_e32 v0, 0
	v_mov_b32_e32 v1, 8
	ds_write_b32 v0, v1
	s_or_b64 exec, exec, s[4:5]
	s_waitcnt lgkmcnt(0)
	s_barrier
	v_readlane_b32 s4, v254, 57
	v_ashrrev_i32_e32 v0, 6, v2
	v_ashrrev_i32_e32 v1, 31, v0
	v_readlane_b32 s5, v254, 58
	s_nop 1
	v_lshl_add_u64 v[10:11], s[4:5], 0, v[0:1]
	s_mov_b64 s[4:5], 0x8000
	v_cmp_gt_u64_e32 vcc, s[4:5], v[10:11]
	s_and_saveexec_b64 s[6:7], vcc
	s_cbranch_execz .LBB0_551
	v_and_b32_e32 v3, 64, v216
	v_add_u32_e32 v3, 64, v3
	v_xor_b32_e32 v4, 32, v216
	v_cmp_lt_i32_e32 vcc, v4, v3
	v_readlane_b32 s4, v255, 22
	v_readlane_b32 s5, v255, 23
	v_cndmask_b32_e32 v4, v216, v4, vcc
	v_lshlrev_b32_e32 v36, 2, v4
	v_xor_b32_e32 v4, 16, v216
	v_cmp_lt_i32_e32 vcc, v4, v3
	s_mov_b32 s9, s5
	s_lshl_b32 s8, s80, 10
	v_cndmask_b32_e32 v4, v216, v4, vcc
	v_lshlrev_b32_e32 v37, 2, v4
	v_xor_b32_e32 v4, 8, v216
	v_cmp_lt_i32_e32 vcc, v4, v3
	v_writelane_b32 v255, s4, 22
	v_readlane_b32 s24, v254, 16
	v_cndmask_b32_e32 v4, v216, v4, vcc
	v_lshlrev_b32_e32 v38, 2, v4
	v_xor_b32_e32 v4, 4, v216
	v_cmp_lt_i32_e32 vcc, v4, v3
	v_writelane_b32 v255, s5, 23
	s_lshl_b64 s[4:5], s[8:9], 2
	v_cndmask_b32_e32 v4, v216, v4, vcc
	v_lshlrev_b32_e32 v39, 2, v4
	v_xor_b32_e32 v4, 2, v216
	v_cmp_lt_i32_e32 vcc, v4, v3
	v_readlane_b32 s25, v254, 17
	s_add_u32 s10, s24, s4
	v_cndmask_b32_e32 v4, v216, v4, vcc
	v_lshlrev_b32_e32 v40, 2, v4
	v_xor_b32_e32 v4, 1, v216
	v_cmp_lt_i32_e32 vcc, v4, v3
	s_addc_u32 s11, s25, s5
	s_add_u32 s4, s86, s4
	v_cndmask_b32_e32 v3, v216, v4, vcc
	v_lshlrev_b32_e32 v41, 2, v3
	v_lshlrev_b32_e32 v3, 4, v2
	s_addc_u32 s5, s87, s5
	v_and_b32_e32 v4, 0x3f0, v3
	v_lshl_add_u64 v[12:13], s[4:5], 0, v[4:5]
	v_lshlrev_b64 v[6:7], 11, v[0:1]
	v_and_b32_e32 v2, 63, v2
	v_readlane_b32 s4, v254, 63
	v_lshl_or_b32 v6, v2, 3, v6
	v_readlane_b32 s5, v255, 0
	s_cmp_eq_u32 s80, 0
	s_mov_b32 s8, s80
	v_readlane_b32 s72, v254, 0
	v_lshl_add_u64 v[16:17], s[4:5], 0, v[6:7]
	v_readlane_b32 s4, v255, 5
	v_readlane_b32 s26, v254, 18
	v_readlane_b32 s27, v254, 19
	v_readlane_b32 s73, v254, 1
	v_readlane_b32 s80, v254, 8
	v_readlane_b32 s81, v254, 9
	v_readlane_b32 s82, v254, 10
	v_readlane_b32 s83, v254, 11
	v_readlane_b32 s84, v254, 12
	v_readlane_b32 s85, v254, 13
	v_readlane_b32 s86, v254, 14
	v_readlane_b32 s87, v254, 15
	v_lshlrev_b64 v[0:1], 12, v[0:1]
	v_readlane_b32 s5, v255, 6
	v_readlane_b32 s80, v255, 24
	s_cselect_b32 s13, s73, s27
	s_cselect_b32 s20, s72, s26
	s_cmp_lg_u32 s8, 3
	v_lshl_add_u64 v[18:19], s[4:5], 0, v[0:1]
	v_readlane_b32 s4, v255, 3
	v_readlane_b32 s78, v254, 6
	v_readlane_b32 s79, v254, 7
	v_readlane_b32 s84, v255, 28
	v_readlane_b32 s85, v255, 29
	s_mov_b32 s80, s8
	s_cselect_b64 s[8:9], -1, 0
	v_readlane_b32 s5, v255, 4
	s_add_u32 s4, s20, s4
	v_readlane_b32 s74, v254, 2
	v_readlane_b32 s75, v254, 3
	v_readlane_b32 s78, v255, 34
	v_readlane_b32 s84, v255, 36
	s_addc_u32 s5, s13, s5
	v_readlane_b32 s79, v255, 35
	v_readlane_b32 s74, v255, 32
	v_readlane_b32 s86, v255, 30
	v_readlane_b32 s87, v255, 31
	v_readlane_b32 s85, v255, 37
	v_lshl_add_u64 v[14:15], s[10:11], 0, v[4:5]
	v_lshlrev_b32_e32 v4, 4, v2
	v_lshl_add_u64 v[20:21], s[4:5], 0, v[0:1]
	s_mov_b64 s[10:11], 0
	v_readlane_b32 s76, v254, 4
	v_readlane_b32 s77, v254, 5
	v_readlane_b32 s75, v255, 33
	v_readlane_b32 s81, v255, 25
	v_readlane_b32 s82, v255, 26
	v_readlane_b32 s83, v255, 27
	v_mov_b32_e32 v67, 0
	v_mov_b32_e32 v68, 1
	v_mov_b32_e32 v70, 0x1000
	v_mov_b32_e32 v71, 0x800
	v_lshrrev_b32_e32 v69, 6, v184
	v_mov_b32_e32 v60, v18
	v_mov_b32_e32 v61, v19
	v_mov_b32_e32 v62, v20
	v_mov_b32_e32 v63, v21
	v_mov_b32_e32 v64, v16
	v_mov_b32_e32 v65, v17
	s_branch .LBB0_543
.LBB0_542:
	s_waitcnt lgkmcnt(0)
	v_readfirstlane_b32 s4, v66
	v_readfirstlane_b32 s21, v69
	s_nop 3
	s_and_b32 s5, s4, 7
	s_lshr_b32 s20, s4, 3
	s_lshl_b32 s20, s20, 11
	s_add_i32 s5, s5, s20
	s_sub_i32 s5, s5, s21
	s_lshl_b32 s4, s4, 8
	v_mov_b32_e32 v10, s4
	v_mov_b32_e32 v11, 0
	v_mad_u64_u32 v[18:19], vcc, s5, v70, v[60:61]
	v_mad_u64_u32 v[20:21], vcc, s5, v70, v[62:63]
	v_mad_u64_u32 v[16:17], vcc, s5, v71, v[64:65]
	s_mov_b64 s[4:5], 0x7fff
	v_cmp_lt_u64_e32 vcc, s[4:5], v[10:11]
	s_or_b64 s[10:11], vcc, s[10:11]
	s_andn2_b64 exec, exec, s[10:11]
	s_cbranch_execz .LBB0_551
; DI unsigned pk2(float lo, float hi) { f32x2 v = {lo, hi}; b16x2 r = __builtin_convertvector(v, b16x2); return __builtin_bit_cast(unsigned, r); }
; DI float bflo(unsigned w) { return __uint_as_float(w << 16); }
; DI float bfhi(unsigned w) { return __uint_as_float(w & 0xffff0000u); }
; DI void phase_ln(const Params& p, int layer) {
;     ...
;   for (size_t row = (size_t)blockIdx.x * 8 + w; row < (size_t)T; row += (size_t)gridDim.x * 8) {
;     f32x4 v[4]; float sum = 0.f;
; #pragma unroll
;     for (int i = 0; i < 4; ++i) {
;       const f32x4 xv = *(const f32x4*)(xres + row * DM + 4 * lane + 256 * i);
;       const u32x2 yw = *(const u32x2*)(xb + row * DM + 4 * lane + 256 * i);
;       v[i][0] = ALPHA * xv[0] + bflo(yw[0]); v[i][1] = ALPHA * xv[1] + bfhi(yw[0]); v[i][2] = ALPHA * xv[2] + bflo(yw[1]); v[i][3] = ALPHA * xv[3] + bfhi(yw[1]);
;       sum += v[i][0] + v[i][1] + v[i][2] + v[i][3];
;     }
;     const float mu = wave_sum(sum) * (1.f / DM);
;     float sq = 0.f;
; #pragma unroll
;     for (int i = 0; i < 4; ++i)
; #pragma unroll
;       for (int j = 0; j < 4; ++j) { float d = v[i][j] - mu; sq += d * d; }
;     const float rstd = rsqrtf(wave_sum(sq) * (1.f / DM) + 1e-5f);
; #pragma unroll
;     for (int i = 0; i < 4; ++i) {
;       const int col = 4 * lane + 256 * i;
;       f32x4 g = *(const f32x4*)(lg + col), bb = *(const f32x4*)(lb + col), o;
; #pragma unroll
;       for (int j = 0; j < 4; ++j) o[j] = (v[i][j] - mu) * rstd * g[j] + bb[j];
;       *(f32x4*)(xout + row * DM + col) = o;
;       if (layer + 1 < DEPTH) {
;         u32x2 ow = {pk2(o[0], o[1]), pk2(o[2], o[3])};
;         *(u32x2*)(xb + row * DM + col) = ow;
;       }
;     }
.LBB0_543:
	s_mov_b64 s[20:21], exec
	s_mov_b64 exec, 1
	ds_add_rtn_u32 v66, v67, v68
	s_mov_b64 exec, s[20:21]
	v_lshl_add_u64 v[22:23], v[20:21], 0, v[4:5]
	global_load_dwordx4 v[30:33], v[22:23], off
	global_load_dwordx2 v[34:35], v[16:17], off offset:-1024
	global_load_dwordx4 v[0:3], v[22:23], off offset:1024
	global_load_dwordx2 v[42:43], v[16:17], off offset:-512
	global_load_dwordx4 v[6:9], v[22:23], off offset:2048
	global_load_dwordx2 v[28:29], v[16:17], off
	global_load_dwordx4 v[24:27], v[22:23], off offset:3072
	global_load_dwordx2 v[44:45], v[16:17], off offset:512
	s_mov_b32 s4, 0x3fd744fd
	s_waitcnt vmcnt(6)
	v_lshlrev_b32_e32 v48, 16, v35
	v_and_b32_e32 v49, 0xffff0000, v35
	v_pk_fma_f32 v[32:33], v[32:33], s[4:5], v[48:49] op_sel_hi:[1,0,1]
	v_lshlrev_b32_e32 v48, 16, v34
	v_and_b32_e32 v49, 0xffff0000, v34
	v_pk_fma_f32 v[30:31], v[30:31], s[4:5], v[48:49] op_sel_hi:[1,0,1]
	s_waitcnt vmcnt(0)
	v_lshlrev_b32_e32 v22, 16, v45
	v_and_b32_e32 v23, 0xffff0000, v45
	v_pk_fma_f32 v[22:23], v[26:27], s[4:5], v[22:23] op_sel_hi:[1,0,1]
	v_lshlrev_b32_e32 v26, 16, v44
	v_and_b32_e32 v27, 0xffff0000, v44
	v_pk_fma_f32 v[24:25], v[24:25], s[4:5], v[26:27] op_sel_hi:[1,0,1]
	v_lshlrev_b32_e32 v26, 16, v29
	v_and_b32_e32 v27, 0xffff0000, v29
	v_pk_fma_f32 v[26:27], v[8:9], s[4:5], v[26:27] op_sel_hi:[1,0,1]
	v_lshlrev_b32_e32 v8, 16, v28
	v_and_b32_e32 v9, 0xffff0000, v28
	v_pk_fma_f32 v[28:29], v[6:7], s[4:5], v[8:9] op_sel_hi:[1,0,1]
	v_mov_b32_e32 v7, v24
	v_mov_b32_e32 v6, v28
	v_mov_b32_e32 v8, v29
	v_mov_b32_e32 v9, v25
	v_pk_add_f32 v[6:7], v[6:7], v[8:9]
	v_mov_b32_e32 v8, v26
	v_mov_b32_e32 v9, v22
	v_pk_add_f32 v[6:7], v[8:9], v[6:7]
	v_mov_b32_e32 v8, v27
	v_mov_b32_e32 v9, v23
	v_pk_add_f32 v[44:45], v[8:9], v[6:7]
	v_lshlrev_b32_e32 v6, 16, v43
	v_and_b32_e32 v7, 0xffff0000, v43
	v_pk_fma_f32 v[46:47], v[2:3], s[4:5], v[6:7] op_sel_hi:[1,0,1]
	v_lshlrev_b32_e32 v2, 16, v42
	v_and_b32_e32 v3, 0xffff0000, v42
	v_pk_fma_f32 v[42:43], v[0:1], s[4:5], v[2:3] op_sel_hi:[1,0,1]
	v_mov_b32_e32 v34, v30
	v_mov_b32_e32 v35, v42
	v_mov_b32_e32 v48, v31
	v_mov_b32_e32 v49, v43
	v_pk_add_f32 v[34:35], v[34:35], v[48:49]
	v_mov_b32_e32 v48, v32
	v_mov_b32_e32 v49, v46
	v_pk_add_f32 v[34:35], v[48:49], v[34:35]
	v_mov_b32_e32 v48, v33
	v_mov_b32_e32 v49, v47
	v_pk_add_f32 v[34:35], v[48:49], v[34:35]
	global_load_dwordx4 v[0:3], v[12:13], off
	global_load_dwordx4 v[6:9], v[14:15], off
	v_add_f32_e32 v34, 0, v34
	v_add_f32_e32 v34, v34, v35
	v_add_f32_e32 v34, v34, v44
	v_add_f32_e32 v34, v34, v45
	ds_bpermute_b32 v35, v36, v34
	s_waitcnt lgkmcnt(0)
	v_add_f32_e32 v34, v34, v35
	ds_bpermute_b32 v35, v37, v34
	s_waitcnt lgkmcnt(0)
	v_add_f32_e32 v34, v34, v35
	ds_bpermute_b32 v35, v38, v34
	s_waitcnt lgkmcnt(0)
	v_add_f32_e32 v34, v34, v35
	ds_bpermute_b32 v35, v39, v34
	s_waitcnt lgkmcnt(0)
	v_add_f32_e32 v34, v34, v35
	ds_bpermute_b32 v35, v40, v34
	s_waitcnt lgkmcnt(0)
	v_add_f32_e32 v34, v34, v35
	ds_bpermute_b32 v35, v41, v34
	s_waitcnt lgkmcnt(0)
	v_add_f32_e32 v34, v34, v35
	v_mul_f32_e32 v34, 0x3a800000, v34
	v_pk_add_f32 v[44:45], v[30:31], v[34:35] op_sel_hi:[1,0] neg_lo:[0,1] neg_hi:[0,1]
	v_pk_add_f32 v[50:51], v[32:33], v[34:35] op_sel_hi:[1,0] neg_lo:[0,1] neg_hi:[0,1]
	v_pk_mul_f32 v[48:49], v[44:45], v[44:45]
	v_pk_mul_f32 v[52:53], v[50:51], v[50:51]
	v_add_f32_e32 v48, v48, v49
	v_pk_add_f32 v[30:31], v[42:43], v[34:35] op_sel_hi:[1,0] neg_lo:[0,1] neg_hi:[0,1]
	v_add_f32_e32 v48, v52, v48
	v_pk_mul_f32 v[42:43], v[30:31], v[30:31]
	v_add_f32_e32 v48, v53, v48
	v_pk_add_f32 v[32:33], v[46:47], v[34:35] op_sel_hi:[1,0] neg_lo:[0,1] neg_hi:[0,1]
	v_add_f32_e32 v42, v42, v48
	v_pk_mul_f32 v[46:47], v[32:33], v[32:33]
	v_add_f32_e32 v42, v43, v42
	v_pk_add_f32 v[28:29], v[28:29], v[34:35] op_sel_hi:[1,0] neg_lo:[0,1] neg_hi:[0,1]
	v_add_f32_e32 v42, v46, v42
	v_pk_mul_f32 v[54:55], v[28:29], v[28:29]
	v_add_f32_e32 v42, v47, v42
	v_pk_add_f32 v[26:27], v[26:27], v[34:35] op_sel_hi:[1,0] neg_lo:[0,1] neg_hi:[0,1]
	v_add_f32_e32 v42, v54, v42
	v_pk_mul_f32 v[56:57], v[26:27], v[26:27]
	v_add_f32_e32 v42, v55, v42
	v_pk_add_f32 v[24:25], v[24:25], v[34:35] op_sel_hi:[1,0] neg_lo:[0,1] neg_hi:[0,1]
	v_add_f32_e32 v42, v56, v42
	v_pk_mul_f32 v[58:59], v[24:25], v[24:25]
	v_add_f32_e32 v42, v57, v42
	v_pk_add_f32 v[22:23], v[22:23], v[34:35] op_sel_hi:[1,0] neg_lo:[0,1] neg_hi:[0,1]
	v_add_f32_e32 v42, v58, v42
	v_pk_mul_f32 v[34:35], v[22:23], v[22:23]
	v_add_f32_e32 v42, v59, v42
	v_add_f32_e32 v34, v34, v42
	v_add_f32_e32 v34, v35, v34
	ds_bpermute_b32 v35, v36, v34
	s_waitcnt lgkmcnt(0)
	v_add_f32_e32 v34, v34, v35
	ds_bpermute_b32 v35, v37, v34
	s_waitcnt lgkmcnt(0)
	v_add_f32_e32 v34, v34, v35
	ds_bpermute_b32 v35, v38, v34
	s_waitcnt lgkmcnt(0)
	v_add_f32_e32 v34, v34, v35
	ds_bpermute_b32 v35, v39, v34
	s_waitcnt lgkmcnt(0)
	v_add_f32_e32 v34, v34, v35
	ds_bpermute_b32 v35, v40, v34
	s_waitcnt lgkmcnt(0)
	v_add_f32_e32 v34, v34, v35
	ds_bpermute_b32 v35, v41, v34
	s_waitcnt lgkmcnt(0)
	v_add_f32_e32 v34, v34, v35
	v_mov_b32_e32 v35, 0x3727c5ac
	v_fmamk_f32 v34, v34, 0x3a800000, v35
	v_cmp_gt_f32_e32 vcc, s65, v34
	v_mul_f32_e32 v35, 0x4b800000, v34
	s_nop 0
	v_cndmask_b32_e32 v34, v34, v35, vcc
	v_rsq_f32_e32 v34, v34
	s_nop 0
	v_mul_f32_e32 v35, 0x45800000, v34
	v_cndmask_b32_e32 v34, v34, v35, vcc
	v_pk_mul_f32 v[42:43], v[44:45], v[34:35] op_sel_hi:[1,0]
	s_andn2_b64 vcc, exec, s[8:9]
	s_waitcnt vmcnt(0)
	v_pk_fma_f32 v[0:1], v[0:1], v[42:43], v[6:7]
	v_pk_mul_f32 v[6:7], v[50:51], v[34:35] op_sel_hi:[1,0]
	s_nop 0
	v_pk_fma_f32 v[2:3], v[2:3], v[6:7], v[8:9]
	v_cndmask_b32_e64 v8, 0, 1, s[8:9]
	v_lshl_add_u64 v[6:7], v[18:19], 0, v[4:5]
	v_cmp_ne_u32_e64 s[4:5], 1, v8
	global_store_dwordx4 v[6:7], v[0:3], off
	s_cbranch_vccnz .LBB0_545
	s_nop 0
	v_cvt_pk_bf16_f32 v0, v0, v1
	v_cvt_pk_bf16_f32 v1, v2, v3
	global_store_dwordx2 v[16:17], v[0:1], off offset:-1024
